# prep x->bf16/rstd: 4 rows per wave processed together (16 loads in flight, interleaved reductions)
# baseline (speedup 1.0000x reference)
; __device__ __forceinline__ void phase_prep(const Params& P, LAS unsigned char* lds) {
;     ...
;     const int wave = tid >> 6, lane = tid & 63; u16* xb = (u16*)(ws + O_XB); float* rstd1 = (float*)(ws + O_RSTD1);
;     for (int chunk = bid; chunk < TALL / 32; chunk += G) {
; #pragma unroll 1
;       for (int rr = 0; rr < 4; ++rr) {
;         const int row = chunk * 32 + wave * 4 + rr;
;         const float* src = row < 65536 ? P.in[I_XP] + (size_t)row * DM : P.in[I_XS] + (size_t)(row - 65536) * DM;
;         f32x4 v[4]; float s = 0.f;
; #pragma unroll
;         for (int j = 0; j < 4; ++j) { v[j] = *(const f32x4*)(src + 4 * lane + 256 * j); s += v[j][0] * v[j][0] + v[j][1] * v[j][1] + v[j][2] * v[j][2] + v[j][3] * v[j][3]; }
; #pragma unroll
;         for (int o = 1; o < 64; o <<= 1) s += __shfl_xor(s, o);
.LBB0_935:
	v_readfirstlane_b32 s0, v4
	v_readlane_b32 s10, v253, 16
	v_readlane_b32 s11, v253, 17
	s_nop 0
	s_cmp_gt_u32 s0, 0xffff
	s_cselect_b32 s10, s10, s36
	s_cselect_b32 s11, s11, s37
	v_mov_b32_e32 v8, v4
	v_ashrrev_i32_e32 v9, 31, v4
	v_lshlrev_b64 v[10:11], 12, v[8:9]
	v_lshl_add_u64 v[10:11], s[10:11], 0, v[10:11]
	v_lshl_add_u64 v[10:11], v[10:11], 0, v[80:81]
	v_mov_b32_e32 v98, 0x1000
	v_mov_b32_e32 v99, 0
	v_lshl_add_u64 v[92:93], v[98:99], 0, v[10:11]
	v_lshl_add_u64 v[94:95], v[98:99], 0, v[92:93]
	v_lshl_add_u64 v[96:97], v[98:99], 0, v[94:95]
	global_load_dwordx4 v[100:103], v[10:11], off
	global_load_dwordx4 v[104:107], v[10:11], off offset:1024
	global_load_dwordx4 v[108:111], v[10:11], off offset:2048
	global_load_dwordx4 v[112:115], v[10:11], off offset:3072
	global_load_dwordx4 v[116:119], v[92:93], off
	global_load_dwordx4 v[120:123], v[92:93], off offset:1024
	global_load_dwordx4 v[124:127], v[92:93], off offset:2048
	global_load_dwordx4 v[128:131], v[92:93], off offset:3072
	global_load_dwordx4 v[132:135], v[94:95], off
	global_load_dwordx4 v[136:139], v[94:95], off offset:1024
	global_load_dwordx4 v[140:143], v[94:95], off offset:2048
	global_load_dwordx4 v[144:147], v[94:95], off offset:3072
	global_load_dwordx4 v[148:151], v[96:97], off
	global_load_dwordx4 v[152:155], v[96:97], off offset:1024
	global_load_dwordx4 v[156:159], v[96:97], off offset:2048
	global_load_dwordx4 v[160:163], v[96:97], off offset:3072
	s_waitcnt vmcnt(12)
	v_mul_f32_e32 v164, v101, v101
	v_mul_f32_e32 v168, v105, v105
	v_mul_f32_e32 v172, v109, v109
	v_fmac_f32_e32 v164, v100, v100
	v_fmac_f32_e32 v168, v104, v104
	v_mul_f32_e32 v176, v113, v113
	v_fmac_f32_e32 v172, v108, v108
	v_fmac_f32_e32 v164, v102, v102
	v_fmac_f32_e32 v168, v106, v106
	v_fmac_f32_e32 v176, v112, v112
	v_fmac_f32_e32 v172, v110, v110
	v_fmac_f32_e32 v164, v103, v103
	v_fmac_f32_e32 v168, v107, v107
	v_fmac_f32_e32 v176, v114, v114
	v_fmac_f32_e32 v172, v111, v111
	v_add_f32_e32 v164, v164, v168
	v_fmac_f32_e32 v176, v115, v115
	v_add_f32_e32 v164, v164, v172
	v_add_f32_e32 v164, v164, v176
	s_waitcnt vmcnt(8)
	v_mul_f32_e32 v165, v117, v117
	v_mul_f32_e32 v169, v121, v121
	v_mul_f32_e32 v173, v125, v125
	v_fmac_f32_e32 v165, v116, v116
	v_fmac_f32_e32 v169, v120, v120
	v_mul_f32_e32 v177, v129, v129
	v_fmac_f32_e32 v173, v124, v124
	v_fmac_f32_e32 v165, v118, v118
	v_fmac_f32_e32 v169, v122, v122
	v_fmac_f32_e32 v177, v128, v128
	v_fmac_f32_e32 v173, v126, v126
	v_fmac_f32_e32 v165, v119, v119
	v_fmac_f32_e32 v169, v123, v123
	v_fmac_f32_e32 v177, v130, v130
	v_fmac_f32_e32 v173, v127, v127
	v_add_f32_e32 v165, v165, v169
	v_fmac_f32_e32 v177, v131, v131
	v_add_f32_e32 v165, v165, v173
	v_add_f32_e32 v165, v165, v177
	s_waitcnt vmcnt(4)
	v_mul_f32_e32 v166, v133, v133
	v_mul_f32_e32 v170, v137, v137
	v_mul_f32_e32 v174, v141, v141
	v_fmac_f32_e32 v166, v132, v132
	v_fmac_f32_e32 v170, v136, v136
	v_mul_f32_e32 v178, v145, v145
	v_fmac_f32_e32 v174, v140, v140
	v_fmac_f32_e32 v166, v134, v134
	v_fmac_f32_e32 v170, v138, v138
	v_fmac_f32_e32 v178, v144, v144
	v_fmac_f32_e32 v174, v142, v142
	v_fmac_f32_e32 v166, v135, v135
	v_fmac_f32_e32 v170, v139, v139
	v_fmac_f32_e32 v178, v146, v146
	v_fmac_f32_e32 v174, v143, v143
	v_add_f32_e32 v166, v166, v170
	v_fmac_f32_e32 v178, v147, v147
	v_add_f32_e32 v166, v166, v174
	v_add_f32_e32 v166, v166, v178
	s_waitcnt vmcnt(0)
	v_mul_f32_e32 v167, v149, v149
	v_mul_f32_e32 v171, v153, v153
	v_mul_f32_e32 v175, v157, v157
	v_fmac_f32_e32 v167, v148, v148
	v_fmac_f32_e32 v171, v152, v152
	v_mul_f32_e32 v179, v161, v161
	v_fmac_f32_e32 v175, v156, v156
	v_fmac_f32_e32 v167, v150, v150
	v_fmac_f32_e32 v171, v154, v154
	v_fmac_f32_e32 v179, v160, v160
	v_fmac_f32_e32 v175, v158, v158
	v_fmac_f32_e32 v167, v151, v151
	v_fmac_f32_e32 v171, v155, v155
	v_fmac_f32_e32 v179, v162, v162
	v_fmac_f32_e32 v175, v159, v159
	v_add_f32_e32 v167, v167, v171
	v_fmac_f32_e32 v179, v163, v163
	v_add_f32_e32 v167, v167, v175
	v_add_f32_e32 v167, v167, v179
	ds_bpermute_b32 v180, v16, v164
	ds_bpermute_b32 v181, v16, v165
	ds_bpermute_b32 v182, v16, v166
	ds_bpermute_b32 v183, v16, v167
	s_waitcnt lgkmcnt(0)
	v_add_f32_e32 v164, v164, v180
	v_add_f32_e32 v165, v165, v181
	v_add_f32_e32 v166, v166, v182
	v_add_f32_e32 v167, v167, v183
	ds_bpermute_b32 v180, v17, v164
	ds_bpermute_b32 v181, v17, v165
	ds_bpermute_b32 v182, v17, v166
	ds_bpermute_b32 v183, v17, v167
	s_waitcnt lgkmcnt(0)
	v_add_f32_e32 v164, v164, v180
	v_add_f32_e32 v165, v165, v181
	v_add_f32_e32 v166, v166, v182
	v_add_f32_e32 v167, v167, v183
	ds_bpermute_b32 v180, v18, v164
	ds_bpermute_b32 v181, v18, v165
	ds_bpermute_b32 v182, v18, v166
	ds_bpermute_b32 v183, v18, v167
	s_waitcnt lgkmcnt(0)
; __device__ __forceinline__ unsigned pk2(float lo, float hi) { const f32x2_t f = {lo, hi}; const bf16x2_t b = __builtin_convertvector(f, bf16x2_t); return __builtin_bit_cast(unsigned, b); }
; __device__ __forceinline__ void phase_prep(const Params& P, LAS unsigned char* lds) {
;     ...
;         for (int o = 1; o < 64; o <<= 1) s += __shfl_xor(s, o);
; #pragma unroll
;         for (int j = 0; j < 4; ++j) { u32x2 o; o.x = pk2(v[j][0], v[j][1]); o.y = pk2(v[j][2], v[j][3]); *(u32x2*)(xb + (size_t)row * DM + 4 * lane + 256 * j) = o; }
;         if (lane == 0) rstd1[row] = rsqrtf(s * (1.0f / 1024.0f) + 1e-6f);
;       }
	v_add_f32_e32 v164, v164, v180
	v_add_f32_e32 v165, v165, v181
	v_add_f32_e32 v166, v166, v182
	v_add_f32_e32 v167, v167, v183
	ds_bpermute_b32 v180, v19, v164
	ds_bpermute_b32 v181, v19, v165
	ds_bpermute_b32 v182, v19, v166
	ds_bpermute_b32 v183, v19, v167
	s_waitcnt lgkmcnt(0)
	v_add_f32_e32 v164, v164, v180
	v_add_f32_e32 v165, v165, v181
	v_add_f32_e32 v166, v166, v182
	v_add_f32_e32 v167, v167, v183
	ds_bpermute_b32 v180, v20, v164
	ds_bpermute_b32 v181, v20, v165
	ds_bpermute_b32 v182, v20, v166
	ds_bpermute_b32 v183, v20, v167
	s_waitcnt lgkmcnt(0)
	v_add_f32_e32 v164, v164, v180
	v_add_f32_e32 v165, v165, v181
	v_add_f32_e32 v166, v166, v182
	v_add_f32_e32 v167, v167, v183
	ds_bpermute_b32 v180, v21, v164
	ds_bpermute_b32 v181, v21, v165
	ds_bpermute_b32 v182, v21, v166
	ds_bpermute_b32 v183, v21, v167
	s_waitcnt lgkmcnt(0)
	v_add_f32_e32 v164, v164, v180
	v_add_f32_e32 v165, v165, v181
	v_add_f32_e32 v166, v166, v182
	v_add_f32_e32 v167, v167, v183
	v_lshlrev_b64 v[12:13], 11, v[8:9]
	v_lshl_add_u64 v[40:41], v[2:3], 0, v[12:13]
	v_lshl_add_u64 v[42:43], v[98:99], 0, v[40:41]
	v_cvt_pk_bf16_f32 v184, v100, v101
	v_cvt_pk_bf16_f32 v185, v102, v103
	v_cvt_pk_bf16_f32 v186, v104, v105
	v_cvt_pk_bf16_f32 v187, v106, v107
	v_cvt_pk_bf16_f32 v188, v108, v109
	v_cvt_pk_bf16_f32 v189, v110, v111
	v_cvt_pk_bf16_f32 v190, v112, v113
	v_cvt_pk_bf16_f32 v191, v114, v115
	v_cvt_pk_bf16_f32 v192, v116, v117
	v_cvt_pk_bf16_f32 v193, v118, v119
	v_cvt_pk_bf16_f32 v194, v120, v121
	v_cvt_pk_bf16_f32 v195, v122, v123
	v_cvt_pk_bf16_f32 v196, v124, v125
	v_cvt_pk_bf16_f32 v197, v126, v127
	v_cvt_pk_bf16_f32 v198, v128, v129
	v_cvt_pk_bf16_f32 v199, v130, v131
	v_cvt_pk_bf16_f32 v200, v132, v133
	v_cvt_pk_bf16_f32 v201, v134, v135
	v_cvt_pk_bf16_f32 v202, v136, v137
	v_cvt_pk_bf16_f32 v203, v138, v139
	v_cvt_pk_bf16_f32 v204, v140, v141
	v_cvt_pk_bf16_f32 v205, v142, v143
	v_cvt_pk_bf16_f32 v206, v144, v145
	v_cvt_pk_bf16_f32 v207, v146, v147
	v_cvt_pk_bf16_f32 v84, v148, v149
	v_cvt_pk_bf16_f32 v85, v150, v151
	v_cvt_pk_bf16_f32 v86, v152, v153
	v_cvt_pk_bf16_f32 v87, v154, v155
	v_cvt_pk_bf16_f32 v88, v156, v157
	v_cvt_pk_bf16_f32 v89, v158, v159
	v_cvt_pk_bf16_f32 v90, v160, v161
	v_cvt_pk_bf16_f32 v91, v162, v163
	flat_store_dwordx2 v[40:41], v[184:185]
	flat_store_dwordx2 v[40:41], v[186:187] offset:512
	flat_store_dwordx2 v[40:41], v[188:189] offset:1024
	flat_store_dwordx2 v[40:41], v[190:191] offset:1536
	flat_store_dwordx2 v[40:41], v[192:193] offset:2048
	flat_store_dwordx2 v[40:41], v[194:195] offset:2560
	flat_store_dwordx2 v[40:41], v[196:197] offset:3072
	flat_store_dwordx2 v[40:41], v[198:199] offset:3584
	flat_store_dwordx2 v[42:43], v[200:201]
	flat_store_dwordx2 v[42:43], v[202:203] offset:512
	flat_store_dwordx2 v[42:43], v[204:205] offset:1024
	flat_store_dwordx2 v[42:43], v[206:207] offset:1536
	flat_store_dwordx2 v[42:43], v[84:85] offset:2048
	flat_store_dwordx2 v[42:43], v[86:87] offset:2560
	flat_store_dwordx2 v[42:43], v[88:89] offset:3072
	flat_store_dwordx2 v[42:43], v[90:91] offset:3584
	s_and_saveexec_b64 s[10:11], vcc
	v_lshl_add_u64 v[12:13], v[8:9], 2, s[6:7]
	v_fmamk_f32 v164, v164, 0x3a800000, v218
	v_mul_f32_e32 v180, 0x4b800000, v164
	v_cmp_gt_f32_e64 s[0:1], s71, v164
	s_nop 1
	v_cndmask_b32_e64 v164, v164, v180, s[0:1]
	v_rsq_f32_e32 v164, v164
	s_nop 0
	v_mul_f32_e32 v180, 0x45800000, v164
	v_cndmask_b32_e64 v164, v164, v180, s[0:1]
	flat_store_dword v[12:13], v164
	v_fmamk_f32 v165, v165, 0x3a800000, v218
	v_mul_f32_e32 v181, 0x4b800000, v165
	v_cmp_gt_f32_e64 s[0:1], s71, v165
	s_nop 1
	v_cndmask_b32_e64 v165, v165, v181, s[0:1]
	v_rsq_f32_e32 v165, v165
	s_nop 0
	v_mul_f32_e32 v181, 0x45800000, v165
	v_cndmask_b32_e64 v165, v165, v181, s[0:1]
	flat_store_dword v[12:13], v165 offset:4
	v_fmamk_f32 v166, v166, 0x3a800000, v218
	v_mul_f32_e32 v182, 0x4b800000, v166
	v_cmp_gt_f32_e64 s[0:1], s71, v166
	s_nop 1
	v_cndmask_b32_e64 v166, v166, v182, s[0:1]
	v_rsq_f32_e32 v166, v166
	s_nop 0
	v_mul_f32_e32 v182, 0x45800000, v166
	v_cndmask_b32_e64 v166, v166, v182, s[0:1]
	flat_store_dword v[12:13], v166 offset:8
	v_fmamk_f32 v167, v167, 0x3a800000, v218
	v_mul_f32_e32 v183, 0x4b800000, v167
	v_cmp_gt_f32_e64 s[0:1], s71, v167
	s_nop 1
	v_cndmask_b32_e64 v167, v167, v183, s[0:1]
	v_rsq_f32_e32 v167, v167
	s_nop 0
	v_mul_f32_e32 v183, 0x45800000, v167
	v_cndmask_b32_e64 v167, v167, v183, s[0:1]
	flat_store_dword v[12:13], v167 offset:12
	s_or_b64 exec, exec, s[10:11]
	s_branch .LBB0_934
